# v37 + code placement: one s_nop 0 before 9 hot loop heads so that all 14 GEMM K loops / attention kv loops start at 0 mod 8 bytes
# speedup vs baseline: 1.0048x; 1.0048x over previous
; template <class Epi>
; __device__ __forceinline__ void gemm_phase(LAS unsigned char* lds, int wave_s, const Gemm g, const StaticOrder S, const Epi E) {
;     ...
;         const bool has_next = S.next(ui + 1, nxt);
;         const char* nA = has_next ? (const char*)g.A + (size_t)nxt.pm * tstepA : cA; const char* nB = has_next ? (const char*)g.Bt + (size_t)nxt.pn * tstepB : cB;
;     ...
; #pragma unroll
;         for (int a = 0; a < 2; ++a)
; #pragma unroll
;             for (int b = 0; b < 2; ++b)
; #pragma unroll
;                 for (int m = 0; m < 4; ++m)
; #pragma unroll
;                     for (int n = 0; n < 2; ++n) acc[a][b][m][n] = (f32x4){0.f, 0.f, 0.f, 0.f};
;         cur = nxt; cA = nA; cB = nB; ++ui;
.LBB0_164:
	s_ashr_i32 s19, s18, 31
	s_lshl_b64 s[6:7], s[18:19], 19
	s_add_u32 s20, s38, s6
	s_addc_u32 s21, s39, s7
	s_and_b64 s[6:7], s[0:1], exec
	s_cselect_b32 s19, s21, s25
	s_cselect_b32 s45, s20, s24
	s_ashr_i32 s17, s16, 31
	s_lshl_b64 s[6:7], s[16:17], 19
	v_readlane_b32 s10, v252, 43
	v_readlane_b32 s11, v252, 44
	s_add_u32 s22, s10, s6
	s_addc_u32 s23, s11, s7
	s_and_b64 s[6:7], s[0:1], exec
	s_cselect_b32 s10, s23, s27
	s_cselect_b32 s11, s22, s26
	s_add_u32 s24, s24, 0x40080
	s_addc_u32 s25, s25, 0
	s_add_u32 s17, s26, 0x100
	v_mov_b32_e32 v2, 0
	s_addc_u32 s46, s27, 0
	s_mov_b32 s47, -2
	v_mov_b32_e32 v246, v2
	v_mov_b32_e32 v247, v2
	v_mov_b32_e32 v248, v2
	v_mov_b32_e32 v249, v2
	v_mov_b32_e32 v3, v2
	v_mov_b32_e32 v4, v2
	v_mfma_f32_32x32x16_bf16 v[18:33], v[246:249], v[246:249], 0
	v_mov_b32_e32 v5, v2
	v_mov_b32_e32 v6, v2
	v_mfma_f32_32x32x16_bf16 v[34:49], v[246:249], v[246:249], 0
	v_mov_b32_e32 v7, v2
	v_mov_b32_e32 v8, v2
	v_mfma_f32_32x32x16_bf16 v[50:65], v[246:249], v[246:249], 0
	v_mov_b32_e32 v9, v2
	v_mov_b32_e32 v10, v2
	v_mfma_f32_32x32x16_bf16 v[66:81], v[246:249], v[246:249], 0
	v_mov_b32_e32 v11, v2
	v_mov_b32_e32 v12, v2
	v_mfma_f32_32x32x16_bf16 v[82:97], v[246:249], v[246:249], 0
	v_mov_b32_e32 v13, v2
	v_mov_b32_e32 v14, v2
	v_mfma_f32_32x32x16_bf16 v[98:113], v[246:249], v[246:249], 0
	v_mov_b32_e32 v15, v2
	v_mov_b32_e32 v16, v2
	v_mfma_f32_32x32x16_bf16 v[114:129], v[246:249], v[246:249], 0
	v_mov_b32_e32 v17, v2
	s_nop 0

; template <class Epi>
; __device__ __forceinline__ void gemm_phase(LAS unsigned char* lds, int wave_s, const Gemm g, const StaticOrder S, const Epi E) {
;     ...
; #pragma unroll
;         for (int a = 0; a < 2; ++a)
; #pragma unroll
;             for (int b = 0; b < 2; ++b)
; #pragma unroll
;                 for (int m = 0; m < 4; ++m)
; #pragma unroll
;                     for (int n = 0; n < 2; ++n) acc[a][b][m][n] = (f32x4){0.f, 0.f, 0.f, 0.f};
;         cur = nxt; cA = nA; cB = nB; ++ui;
.LBB0_564:
	s_add_u32 s10, s20, 0x100
	v_mov_b32_e32 v2, 0
	s_addc_u32 s11, s21, 0
	s_mov_b32 s50, -2
	v_mov_b32_e32 v246, v2
	v_mov_b32_e32 v247, v2
	v_mov_b32_e32 v248, v2
	v_mov_b32_e32 v249, v2
	v_mov_b32_e32 v3, v2
	v_mov_b32_e32 v4, v2
	v_mfma_f32_32x32x16_bf16 v[18:33], v[246:249], v[246:249], 0
	v_mov_b32_e32 v5, v2
	v_mov_b32_e32 v6, v2
	v_mfma_f32_32x32x16_bf16 v[34:49], v[246:249], v[246:249], 0
	v_mov_b32_e32 v7, v2
	v_mov_b32_e32 v8, v2
	v_mfma_f32_32x32x16_bf16 v[50:65], v[246:249], v[246:249], 0
	v_mov_b32_e32 v9, v2
	v_mov_b32_e32 v10, v2
	v_mfma_f32_32x32x16_bf16 v[66:81], v[246:249], v[246:249], 0
	v_mov_b32_e32 v11, v2
	v_mov_b32_e32 v12, v2
	v_mfma_f32_32x32x16_bf16 v[82:97], v[246:249], v[246:249], 0
	v_mov_b32_e32 v13, v2
	v_mov_b32_e32 v14, v2
	v_mfma_f32_32x32x16_bf16 v[98:113], v[246:249], v[246:249], 0
	v_mov_b32_e32 v15, v2
	v_mov_b32_e32 v16, v2
	v_mfma_f32_32x32x16_bf16 v[114:129], v[246:249], v[246:249], 0
	v_mov_b32_e32 v17, v2
	s_nop 0

; template <class Epi>
; __device__ __forceinline__ void gemm_phase(LAS unsigned char* lds, int wave_s, const Gemm g, const StaticOrder S, const Epi E) {
;     ...
;         const bool has_next = S.next(ui + 1, nxt);
;         const char* nA = has_next ? (const char*)g.A + (size_t)nxt.pm * tstepA : cA; const char* nB = has_next ? (const char*)g.Bt + (size_t)nxt.pn * tstepB : cB;
;     ...
; #pragma unroll
;         for (int a = 0; a < 2; ++a)
; #pragma unroll
;             for (int b = 0; b < 2; ++b)
; #pragma unroll
;                 for (int m = 0; m < 4; ++m)
; #pragma unroll
;                     for (int n = 0; n < 2; ++n) acc[a][b][m][n] = (f32x4){0.f, 0.f, 0.f, 0.f};
;         cur = nxt; cA = nA; cB = nB; ++ui;
.LBB0_634:
	s_ashr_i32 s17, s16, 31
	s_lshl_b64 s[6:7], s[16:17], 17
	v_readlane_b32 s10, v255, 55
	v_readlane_b32 s11, v255, 56
	s_add_u32 s20, s10, s6
	s_addc_u32 s21, s11, s7
	s_and_b64 s[0:1], s[0:1], exec
	v_mov_b32_e32 v2, 0
	s_cselect_b32 s17, s21, s23
	s_cselect_b32 s10, s20, s22
	s_mov_b32 s11, 0
	s_mov_b64 s[0:1], -1
	s_mov_b64 s[26:27], 0
	v_mov_b32_e32 v246, v2
	v_mov_b32_e32 v247, v2
	v_mov_b32_e32 v248, v2
	v_mov_b32_e32 v249, v2
	v_mov_b32_e32 v3, v2
	v_mov_b32_e32 v4, v2
	v_mfma_f32_32x32x16_bf16 v[18:33], v[246:249], v[246:249], 0
	v_mov_b32_e32 v5, v2
	v_mov_b32_e32 v6, v2
	v_mfma_f32_32x32x16_bf16 v[34:49], v[246:249], v[246:249], 0
	v_mov_b32_e32 v7, v2
	v_mov_b32_e32 v8, v2
	v_mfma_f32_32x32x16_bf16 v[50:65], v[246:249], v[246:249], 0
	v_mov_b32_e32 v9, v2
	v_mov_b32_e32 v10, v2
	v_mfma_f32_32x32x16_bf16 v[66:81], v[246:249], v[246:249], 0
	v_mov_b32_e32 v11, v2
	v_mov_b32_e32 v12, v2
	v_mfma_f32_32x32x16_bf16 v[82:97], v[246:249], v[246:249], 0
	v_mov_b32_e32 v13, v2
	v_mov_b32_e32 v14, v2
	v_mfma_f32_32x32x16_bf16 v[98:113], v[246:249], v[246:249], 0
	v_mov_b32_e32 v15, v2
	v_mov_b32_e32 v16, v2
	v_mfma_f32_32x32x16_bf16 v[114:129], v[246:249], v[246:249], 0
	v_mov_b32_e32 v17, v2
	s_nop 0

;     ...
;     bf16x8 qf[DQK / 16];
;     { const bf16_t* qrow = Qp + (size_t)(32 * wid + r32) * qpitch + 8 * h;
; #pragma unroll
;       for (int d0 = 0; d0 < DQK / 16; ++d0) qf[d0] = *(const bf16x8*)(qrow + 16 * d0); }
;     float mrun = -INFINITY, lrun = 0.f;
; #pragma unroll
;     for (int db = 0; db < NDB; ++db)
; #pragma unroll
;         for (int r = 0; r < 16; ++r) o[db][r] = 0.f;
;     const int qw0 = q0 + 32 * wid, qpos = qw0 + r32;
;     ...
;         FA_QK(pA0, pA1, kt_lo - win_lo, zero16);
.LBB0_828:
	s_or_b64 exec, exec, s[12:13]
	s_add_i32 s40, s44, s57
	s_lshl_b64 s[6:7], s[40:41], 2
	s_add_u32 s6, s84, s6
	s_addc_u32 s7, s85, s7
	s_waitcnt lgkmcnt(0)
	s_barrier
	global_load_dword v122, v1, s[6:7]
	s_lshl_b32 s4, s44, 7
	v_mbcnt_lo_u32_b32 v2, -1, 0
	v_mbcnt_hi_u32_b32 v2, -1, v2
	s_add_u32 s6, s25, s4
	v_add_u32_e32 v0, s92, v2
	s_addc_u32 s7, s26, 0
	v_readfirstlane_b32 s4, v0
	s_ashr_i32 s4, s4, 1
	v_bfe_u32 v3, v2, 5, 1
	v_mov_b32_e32 v0, s4
	v_bfi_b32 v0, s42, v0, v2
	v_mov_b64_e32 v[4:5], s[6:7]
	v_mad_i64_i32 v[4:5], s[6:7], v0, s52, v[4:5]
	v_lshlrev_b32_e32 v0, 4, v3
	v_lshl_add_u64 v[4:5], v[4:5], 0, v[0:1]
	global_load_dwordx4 v[98:101], v[4:5], off offset:1536
	global_load_dwordx4 v[102:105], v[4:5], off offset:1568
	global_load_dwordx4 v[106:109], v[4:5], off offset:1600
	global_load_dwordx4 v[110:113], v[4:5], off offset:1632
	v_and_b32_e32 v4, 31, v2
	v_mul_u32_u24_e32 v5, 0x90, v4
	v_add3_u32 v10, s27, v5, v0
	ds_read_b128 v[6:9], v10
	s_andn2_b64 vcc, exec, s[0:1]
	s_waitcnt vmcnt(3) lgkmcnt(0)
	v_mfma_f32_32x32x16_bf16 v[52:67], v[6:9], v[98:101], 0
	ds_read_b128 v[6:9], v10 offset:4608
	s_waitcnt lgkmcnt(0)
	v_mfma_f32_32x32x16_bf16 v[68:83], v[6:9], v[98:101], 0
	ds_read_b128 v[6:9], v10 offset:32
	s_waitcnt vmcnt(2) lgkmcnt(0)
	v_mfma_f32_32x32x16_bf16 v[52:67], v[6:9], v[102:105], v[52:67]
	ds_read_b128 v[6:9], v10 offset:4640
	s_waitcnt lgkmcnt(0)
	v_mfma_f32_32x32x16_bf16 v[68:83], v[6:9], v[102:105], v[68:83]
	ds_read_b128 v[6:9], v10 offset:64
	s_waitcnt vmcnt(1) lgkmcnt(0)
	v_mfma_f32_32x32x16_bf16 v[52:67], v[6:9], v[106:109], v[52:67]
	ds_read_b128 v[6:9], v10 offset:4672
	s_waitcnt lgkmcnt(0)
	v_mfma_f32_32x32x16_bf16 v[68:83], v[6:9], v[106:109], v[68:83]
	ds_read_b128 v[6:9], v10 offset:96
	s_waitcnt vmcnt(0) lgkmcnt(0)
	v_mfma_f32_32x32x16_bf16 v[52:67], v[6:9], v[110:113], v[52:67]
	ds_read_b128 v[6:9], v10 offset:4704
	s_waitcnt lgkmcnt(0)
	v_mfma_f32_32x32x16_bf16 v[68:83], v[6:9], v[110:113], v[68:83]
	s_cbranch_vccnz .LBB0_819
	v_lshlrev_b32_e32 v6, 1, v2
	v_lshlrev_b32_e32 v7, 3, v2
	v_lshlrev_b32_e32 v2, 4, v2
	s_andn2_b32 s4, s4, 31
	v_lshlrev_b32_e32 v3, 8, v3
	v_and_b32_e32 v2, 0xc0, v2
	v_and_b32_e32 v6, 32, v6
	v_and_b32_e32 v7, 24, v7
	v_add3_u32 v2, s30, v3, v2
	s_add_i32 s4, s23, s4
	v_add3_u32 v123, 0, v5, v0
	v_add3_u32 v124, v2, v6, v7
	v_add_u32_e32 v0, s31, v0
	v_add_lshl_u32 v2, s4, v4, 2
	v_sub_u32_e32 v125, v0, v2
	v_mov_b32_e32 v2, v1
	v_mov_b32_e32 v3, v1
	v_mov_b32_e32 v4, v1
	v_mov_b32_e32 v5, v1
	v_mov_b32_e32 v6, v1
	v_mov_b32_e32 v7, v1
	v_mov_b32_e32 v8, v1
	v_mov_b32_e32 v9, v1
	v_mov_b32_e32 v10, v1
	v_mov_b32_e32 v11, v1
	v_mov_b32_e32 v12, v1
	v_mov_b32_e32 v13, v1
	v_mov_b32_e32 v14, v1
	v_mov_b32_e32 v15, v1
	v_mov_b32_e32 v16, v1
	v_mov_b32_e32 v17, v1
	v_mov_b32_e32 v18, v1
	v_mov_b32_e32 v19, v1
	v_mov_b32_e32 v20, v1
	v_mov_b32_e32 v21, v1
	v_mov_b32_e32 v22, v1
	v_mov_b32_e32 v23, v1
	v_mov_b32_e32 v24, v1
	v_mov_b32_e32 v25, v1
	v_mov_b32_e32 v26, v1
	v_mov_b32_e32 v27, v1
	v_mov_b32_e32 v28, v1
	v_mov_b32_e32 v29, v1
	v_mov_b32_e32 v30, v1
	v_mov_b32_e32 v31, v1
	v_mov_b32_e32 v0, v1
	v_mov_b64_e32 v[32:33], v[30:31]
	v_mov_b32_e32 v34, 0
	v_mov_b32_e32 v127, 0xff800000
	v_mov_b64_e32 v[30:31], v[28:29]
	v_mov_b64_e32 v[28:29], v[26:27]
	v_mov_b64_e32 v[26:27], v[24:25]
	v_mov_b64_e32 v[24:25], v[22:23]
	v_mov_b64_e32 v[22:23], v[20:21]
	v_mov_b64_e32 v[20:21], v[18:19]
	v_mov_b64_e32 v[18:19], v[16:17]
	v_mov_b64_e32 v[16:17], v[14:15]
	v_mov_b64_e32 v[14:15], v[12:13]
	v_mov_b64_e32 v[12:13], v[10:11]
	v_mov_b64_e32 v[10:11], v[8:9]
	v_mov_b64_e32 v[8:9], v[6:7]
	v_mov_b64_e32 v[6:7], v[4:5]
	v_mov_b64_e32 v[4:5], v[2:3]
	v_mov_b64_e32 v[2:3], v[0:1]
	s_mov_b32 s12, s21
	s_branch .LBB0_831
	s_nop 0

;     ...
;     float mrun = -INFINITY, lrun = 0.f;
; #pragma unroll
;     for (int db = 0; db < NDB; ++db)
; #pragma unroll
;         for (int r = 0; r < 16; ++r) o[db][r] = 0.f;
;     ...
;         if (NEGM) { if (MODE == 2) {     const int tl0 = 64 * kt_lo; float c0_ = 0.f; if (tl0 + 63 - qw0 <= -128) c0_ = lut[0]; else if (tl0 - (qw0 + 31) >= 128) c0_ = lut[511]; cbs = c0_;
; #pragma unroll
;         for (int r_ = 0; r_ < 16; ++r_) negc[r_] = c0_; } }
;         FA_QK(pA0, pA1, 0, negc);
;         __syncthreads();
.LBB0_919:
	v_and_b32_e32 v21, 31, v19
	s_movk_i32 s0, 0x90
	v_mad_u32_u24 v2, v21, s0, 0
	v_add_u32_e32 v215, v2, v0
	ds_read_b128 v[2:5], v215
	ds_read_b128 v[6:9], v215 offset:32
	s_waitcnt lgkmcnt(2)
	v_mov_b32_e32 v113, v112
	v_mov_b32_e32 v114, v112
	v_mov_b32_e32 v115, v112
	v_mov_b32_e32 v116, v112
	v_mov_b32_e32 v117, v112
	v_mov_b32_e32 v118, v112
	v_mov_b32_e32 v119, v112
	v_mov_b32_e32 v120, v112
	v_mov_b32_e32 v121, v112
	v_mov_b32_e32 v122, v112
	v_mov_b32_e32 v123, v112
	v_mov_b32_e32 v124, v112
	v_mov_b32_e32 v125, v112
	v_mov_b32_e32 v126, v112
	v_mov_b32_e32 v127, v112
	v_mov_b64_e32 v[80:81], v[112:113]
	v_mov_b64_e32 v[82:83], v[114:115]
	s_waitcnt lgkmcnt(1)
	v_mfma_f32_32x32x16_bf16 v[128:143], v[2:5], v[176:179], v[112:127]
	ds_read_b128 v[2:5], v215 offset:4608
	v_mov_b64_e32 v[84:85], v[116:117]
	v_mov_b64_e32 v[86:87], v[118:119]
	v_mov_b64_e32 v[88:89], v[120:121]
	v_mov_b64_e32 v[90:91], v[122:123]
	v_mov_b64_e32 v[92:93], v[124:125]
	v_mov_b64_e32 v[94:95], v[126:127]
	s_waitcnt vmcnt(0)
	ds_read_b128 v[10:13], v215 offset:4640
	s_waitcnt lgkmcnt(2)
	v_mfma_f32_32x32x16_bf16 v[128:143], v[6:9], v[180:183], v[128:143]
	v_lshlrev_b32_e32 v6, 1, v19
	v_mad_i64_i32 v[16:17], s[0:1], v20, s7, 0
	v_and_b32_e32 v20, 32, v6
	v_lshlrev_b32_e32 v6, 3, v19
	v_and_b32_e32 v22, 24, v6
	v_lshlrev_b32_e32 v19, 4, v19
	s_waitcnt lgkmcnt(1)
	v_mfma_f32_32x32x16_bf16 v[80:95], v[2:5], v[176:179], v[80:95]
	ds_read_b128 v[2:5], v215 offset:64
	s_and_b32 s29, s23, 0x700
	s_and_b32 s0, s4, 7
	s_add_i32 s4, s29, s6
	s_lshl_b32 s25, s10, 7
	s_lshl_b32 s30, s0, 8
	s_sub_i32 s31, 0xbf, s4
	s_waitcnt lgkmcnt(1)
	v_mfma_f32_32x32x16_bf16 v[80:95], v[10:13], v[180:183], v[80:95]
	ds_read_b128 v[6:9], v215 offset:4672
	ds_read_b128 v[10:13], v215 offset:96
	s_add_u32 s0, s30, s27
	s_addc_u32 s1, 0, s26
	s_mov_b64 s[20:21], 0
	v_mov_b32_e32 v217, 0
	v_mov_b32_e32 v160, v112
	v_mov_b32_e32 v161, v112
	s_waitcnt lgkmcnt(2)
	v_mfma_f32_32x32x16_bf16 v[128:143], v[2:5], v[184:187], v[128:143]
	v_and_b32_e32 v2, 0xc0, v19
	v_lshl_or_b32 v2, v18, 8, v2
	v_or3_b32 v18, v2, v20, v22
	ds_read_b128 v[2:5], v215 offset:4704
	v_add_u32_e32 v113, 0, v18
	v_mov_b32_e32 v162, v112
	v_mov_b32_e32 v163, v112
	s_waitcnt lgkmcnt(2)
	v_mfma_f32_32x32x16_bf16 v[80:95], v[6:9], v[184:187], v[80:95]
	v_lshl_add_u64 v[6:7], s[0:1], 0, v[16:17]
	v_readlane_b32 s0, v254, 1
	v_lshl_add_u64 v[6:7], v[14:15], 1, v[6:7]
	v_readlane_b32 s1, v254, 2
	v_mov_b32_e32 v14, v1
	v_mov_b32_e32 v15, v1
	v_lshl_add_u64 v[212:213], s[0:1], 0, v[6:7]
	s_waitcnt lgkmcnt(1)
	v_mfma_f32_32x32x16_bf16 v[128:143], v[10:13], v[188:191], v[128:143]
	v_add_lshl_u32 v6, s4, v21, 2
	v_sub_u32_e32 v0, v0, v6
	v_readlane_b32 s0, v254, 5
	v_mov_b32_e32 v6, v1
	v_mov_b32_e32 v7, v1
	v_add_u32_e32 v216, s0, v0
	v_mov_b32_e32 v0, v1
	s_waitcnt lgkmcnt(0)
	v_mfma_f32_32x32x16_bf16 v[80:95], v[2:5], v[188:191], v[80:95]
	v_mov_b32_e32 v2, v1
	v_mov_b32_e32 v3, v1
	v_mov_b32_e32 v4, v1
	v_mov_b32_e32 v5, v1
	v_mov_b32_e32 v8, v1
	v_mov_b32_e32 v9, v1
	v_mov_b32_e32 v10, v1
	v_mov_b32_e32 v11, v1
	v_mov_b32_e32 v12, v1
	v_mov_b32_e32 v13, v1
	v_mov_b64_e32 v[30:31], v[14:15]
	v_mov_b64_e32 v[46:47], v[14:15]
	v_mov_b64_e32 v[62:63], v[14:15]
	v_mov_b64_e32 v[78:79], v[14:15]
	s_mov_b32 s4, -2
	v_mov_b64_e32 v[28:29], v[12:13]
	v_mov_b64_e32 v[26:27], v[10:11]
	v_mov_b64_e32 v[24:25], v[8:9]
	v_mov_b64_e32 v[22:23], v[6:7]
	v_mov_b64_e32 v[20:21], v[4:5]
	v_mov_b64_e32 v[18:19], v[2:3]
	v_mov_b64_e32 v[16:17], v[0:1]
	v_mov_b64_e32 v[44:45], v[12:13]
	v_mov_b64_e32 v[42:43], v[10:11]
	v_mov_b64_e32 v[40:41], v[8:9]
	v_mov_b64_e32 v[38:39], v[6:7]
	v_mov_b64_e32 v[36:37], v[4:5]
	v_mov_b64_e32 v[34:35], v[2:3]
	v_mov_b64_e32 v[32:33], v[0:1]
	v_mov_b64_e32 v[60:61], v[12:13]
	v_mov_b64_e32 v[58:59], v[10:11]
	v_mov_b64_e32 v[56:57], v[8:9]
	v_mov_b64_e32 v[54:55], v[6:7]
	v_mov_b64_e32 v[52:53], v[4:5]
	v_mov_b64_e32 v[50:51], v[2:3]
	v_mov_b64_e32 v[48:49], v[0:1]
	v_mov_b64_e32 v[76:77], v[12:13]
	v_mov_b64_e32 v[74:75], v[10:11]
	v_mov_b64_e32 v[72:73], v[8:9]
	v_mov_b64_e32 v[70:71], v[6:7]
	v_mov_b64_e32 v[68:69], v[4:5]
	v_mov_b64_e32 v[66:67], v[2:3]
	v_mov_b64_e32 v[64:65], v[0:1]
	v_mov_b32_e32 v15, 0
	v_mov_b32_e32 v0, 0
	v_mov_b32_e32 v164, v112
	v_mov_b32_e32 v165, v112
	v_mov_b32_e32 v166, v112
	v_mov_b32_e32 v167, v112
	v_mov_b32_e32 v168, v112
	v_mov_b32_e32 v169, v112
	v_mov_b32_e32 v170, v112
	v_mov_b32_e32 v171, v112
	v_mov_b32_e32 v172, v112
	v_mov_b32_e32 v173, v112
	v_mov_b32_e32 v174, v112
	v_mov_b32_e32 v175, v112
	s_barrier
	ds_read_b32 v0, v1 offset:61440
	s_waitcnt lgkmcnt(0)
	v_readfirstlane_b32 s100, v0
	ds_read_b32 v0, v1 offset:63484
	s_waitcnt lgkmcnt(0)
	v_readfirstlane_b32 s101, v0
	v_mov_b32_e32 v0, 0
	s_add_i32 s0, s31, 0xfffffea2
	s_cmp_lt_u32 s0, 0xfffffea3
	s_cbranch_scc0 .LBB0_925
	s_nop 0

; template <class Epi>
; __device__ __forceinline__ void gemm_phase(LAS unsigned char* lds, int wave_s, const Gemm g, const StaticOrder S, const Epi E) {
;     ...
;         const bool has_next = S.next(ui + 1, nxt);
;         const char* nA = has_next ? (const char*)g.A + (size_t)nxt.pm * tstepA : cA; const char* nB = has_next ? (const char*)g.Bt + (size_t)nxt.pn * tstepB : cB;
;     ...
; #pragma unroll
;         for (int a = 0; a < 2; ++a)
; #pragma unroll
;             for (int b = 0; b < 2; ++b)
; #pragma unroll
;                 for (int m = 0; m < 4; ++m)
; #pragma unroll
;                     for (int n = 0; n < 2; ++n) acc[a][b][m][n] = (f32x4){0.f, 0.f, 0.f, 0.f};
;         cur = nxt; cA = nA; cB = nB; ++ui;
.LBB0_1067:
	s_ashr_i32 s21, s20, 31
	s_lshl_b64 s[6:7], s[20:21], 19
	v_readlane_b32 s10, v253, 6
	v_readlane_b32 s11, v253, 7
	s_add_u32 s24, s10, s6
	s_addc_u32 s25, s11, s7
	s_and_b64 s[0:1], s[0:1], exec
	s_cselect_b32 s10, s25, s29
	s_cselect_b32 s11, s24, s28
	s_add_u32 s21, s28, 0x100
	v_mov_b32_e32 v2, 0
	s_addc_u32 s52, s29, 0
	s_mov_b32 s53, -2
	v_mov_b32_e32 v246, v2
	v_mov_b32_e32 v247, v2
	v_mov_b32_e32 v248, v2
	v_mov_b32_e32 v249, v2
	v_mov_b32_e32 v3, v2
	v_mov_b32_e32 v4, v2
	v_mfma_f32_32x32x16_bf16 v[18:33], v[246:249], v[246:249], 0
	v_mov_b32_e32 v5, v2
	v_mov_b32_e32 v6, v2
	v_mfma_f32_32x32x16_bf16 v[34:49], v[246:249], v[246:249], 0
	v_mov_b32_e32 v7, v2
	v_mov_b32_e32 v8, v2
	v_mfma_f32_32x32x16_bf16 v[50:65], v[246:249], v[246:249], 0
	v_mov_b32_e32 v9, v2
	v_mov_b32_e32 v10, v2
	v_mfma_f32_32x32x16_bf16 v[66:81], v[246:249], v[246:249], 0
	v_mov_b32_e32 v11, v2
	v_mov_b32_e32 v12, v2
	v_mfma_f32_32x32x16_bf16 v[82:97], v[246:249], v[246:249], 0
	v_mov_b32_e32 v13, v2
	v_mov_b32_e32 v14, v2
	v_mfma_f32_32x32x16_bf16 v[98:113], v[246:249], v[246:249], 0
	v_mov_b32_e32 v15, v2
	v_mov_b32_e32 v16, v2
	v_mfma_f32_32x32x16_bf16 v[114:129], v[246:249], v[246:249], 0
	v_mov_b32_e32 v17, v2
	s_nop 0

; template <class Epi>
; __device__ __forceinline__ void gemm_phase(LAS unsigned char* lds, int wave_s, const Gemm g, const StaticOrder S, const Epi E) {
;     ...
;         const bool has_next = S.next(ui + 1, nxt);
;         const char* nA = has_next ? (const char*)g.A + (size_t)nxt.pm * tstepA : cA; const char* nB = has_next ? (const char*)g.Bt + (size_t)nxt.pn * tstepB : cB;
;     ...
; #pragma unroll
;         for (int a = 0; a < 2; ++a)
; #pragma unroll
;             for (int b = 0; b < 2; ++b)
; #pragma unroll
;                 for (int m = 0; m < 4; ++m)
; #pragma unroll
;                     for (int n = 0; n < 2; ++n) acc[a][b][m][n] = (f32x4){0.f, 0.f, 0.f, 0.f};
;         cur = nxt; cA = nA; cB = nB; ++ui;
.LBB0_1150:
	s_ashr_i32 s17, s16, 31
	s_lshl_b64 s[6:7], s[16:17], 19
	v_readlane_b32 s10, v253, 35
	v_readlane_b32 s11, v253, 36
	s_add_u32 s18, s10, s6
	s_addc_u32 s19, s11, s7
	s_and_b64 s[6:7], s[42:43], exec
	s_cselect_b32 s17, s19, s23
	s_cselect_b32 s40, s18, s22
	s_ashr_i32 s15, s14, 31
	s_lshl_b64 s[6:7], s[14:15], 19
	v_readlane_b32 s10, v252, 54
	v_readlane_b32 s11, v252, 55
	s_add_u32 s20, s10, s6
	s_addc_u32 s21, s11, s7
	s_and_b64 s[6:7], s[42:43], exec
	s_cselect_b32 s10, s21, s25
	s_cselect_b32 s11, s20, s24
	s_add_u32 s22, s22, 0x40080
	s_addc_u32 s23, s23, 0
	s_add_u32 s15, s24, 0x100
	v_mov_b32_e32 v2, 0
	s_addc_u32 s44, s25, 0
	s_mov_b32 s45, -2
	v_mov_b32_e32 v246, v2
	v_mov_b32_e32 v247, v2
	v_mov_b32_e32 v248, v2
	v_mov_b32_e32 v249, v2
	v_mov_b32_e32 v3, v2
	v_mov_b32_e32 v4, v2
	v_mfma_f32_32x32x16_bf16 v[18:33], v[246:249], v[246:249], 0
	v_mov_b32_e32 v5, v2
	v_mov_b32_e32 v6, v2
	v_mfma_f32_32x32x16_bf16 v[34:49], v[246:249], v[246:249], 0
	v_mov_b32_e32 v7, v2
	v_mov_b32_e32 v8, v2
	v_mfma_f32_32x32x16_bf16 v[50:65], v[246:249], v[246:249], 0
	v_mov_b32_e32 v9, v2
	v_mov_b32_e32 v10, v2
	v_mfma_f32_32x32x16_bf16 v[66:81], v[246:249], v[246:249], 0
	v_mov_b32_e32 v11, v2
	v_mov_b32_e32 v12, v2
	v_mfma_f32_32x32x16_bf16 v[82:97], v[246:249], v[246:249], 0
	v_mov_b32_e32 v13, v2
	v_mov_b32_e32 v14, v2
	v_mfma_f32_32x32x16_bf16 v[98:113], v[246:249], v[246:249], 0
	v_mov_b32_e32 v15, v2
	v_mov_b32_e32 v16, v2
	v_mfma_f32_32x32x16_bf16 v[114:129], v[246:249], v[246:249], 0
	v_mov_b32_e32 v17, v2
	s_nop 0

; template <class Epi>
; __device__ __forceinline__ void gemm_phase(LAS unsigned char* lds, int wave_s, const Gemm g, const StaticOrder S, const Epi E) {
;     ...
;         const bool has_next = S.next(ui + 1, nxt);
;         const char* nA = has_next ? (const char*)g.A + (size_t)nxt.pm * tstepA : cA; const char* nB = has_next ? (const char*)g.Bt + (size_t)nxt.pn * tstepB : cB;
;     ...
; #pragma unroll
;         for (int a = 0; a < 2; ++a)
; #pragma unroll
;             for (int b = 0; b < 2; ++b)
; #pragma unroll
;                 for (int m = 0; m < 4; ++m)
; #pragma unroll
;                     for (int n = 0; n < 2; ++n) acc[a][b][m][n] = (f32x4){0.f, 0.f, 0.f, 0.f};
;         cur = nxt; cA = nA; cB = nB; ++ui;
.LBB0_1170:
	s_ashr_i32 s17, s16, 31
	s_lshl_b64 s[0:1], s[16:17], 17
	s_add_u32 s18, s20, s0
	s_addc_u32 s19, s21, s1
	s_and_b64 s[0:1], s[42:43], exec
	s_cselect_b32 s17, s19, s25
	s_cselect_b32 s56, s18, s24
	s_ashr_i32 s15, s14, 31
	s_lshl_b64 s[0:1], s[14:15], 17
	v_readlane_b32 s6, v255, 4
	v_readlane_b32 s7, v255, 5
	s_add_u32 s20, s6, s0
	s_addc_u32 s21, s7, s1
	s_and_b64 s[0:1], s[42:43], exec
	v_mov_b32_e32 v2, 0
	s_cselect_b32 s15, s21, s23
	s_cselect_b32 s10, s20, s22
	s_mov_b32 s11, 0
	s_mov_b64 s[26:27], -1
	s_mov_b64 s[28:29], 0
	v_mov_b32_e32 v246, v2
	v_mov_b32_e32 v247, v2
	v_mov_b32_e32 v248, v2
	v_mov_b32_e32 v249, v2
	v_mov_b32_e32 v3, v2
	v_mov_b32_e32 v4, v2
	v_mfma_f32_32x32x16_bf16 v[18:33], v[246:249], v[246:249], 0
	v_mov_b32_e32 v5, v2
	v_mov_b32_e32 v6, v2
	v_mfma_f32_32x32x16_bf16 v[34:49], v[246:249], v[246:249], 0
	v_mov_b32_e32 v7, v2
	v_mov_b32_e32 v8, v2
	v_mfma_f32_32x32x16_bf16 v[50:65], v[246:249], v[246:249], 0
	v_mov_b32_e32 v9, v2
	v_mov_b32_e32 v10, v2
	v_mfma_f32_32x32x16_bf16 v[66:81], v[246:249], v[246:249], 0
	v_mov_b32_e32 v11, v2
	v_mov_b32_e32 v12, v2
	v_mfma_f32_32x32x16_bf16 v[82:97], v[246:249], v[246:249], 0
	v_mov_b32_e32 v13, v2
	v_mov_b32_e32 v14, v2
	v_mfma_f32_32x32x16_bf16 v[98:113], v[246:249], v[246:249], 0
	v_mov_b32_e32 v15, v2
	v_mov_b32_e32 v16, v2
	v_mfma_f32_32x32x16_bf16 v[114:129], v[246:249], v[246:249], 0
	v_mov_b32_e32 v17, v2
	s_nop 0

; template <class Epi>
; __device__ __forceinline__ void gemm_phase(LAS unsigned char* lds, int wave_s, const Gemm g, const StaticOrder S, const Epi E) {
;     ...
; #pragma unroll
;         for (int a = 0; a < 2; ++a)
; #pragma unroll
;             for (int b = 0; b < 2; ++b)
; #pragma unroll
;                 for (int m = 0; m < 4; ++m)
; #pragma unroll
;                     for (int n = 0; n < 2; ++n) acc[a][b][m][n] = (f32x4){0.f, 0.f, 0.f, 0.f};
;         cur = nxt; cA = nA; cB = nB; ++ui;
.LBB0_1246:
	s_add_u32 s10, s14, 0x100
	v_mov_b32_e32 v2, 0
	s_addc_u32 s11, s15, 0
	s_mov_b32 s34, -2
	v_mov_b32_e32 v246, v2
	v_mov_b32_e32 v247, v2
	v_mov_b32_e32 v248, v2
	v_mov_b32_e32 v249, v2
	v_mov_b32_e32 v3, v2
	v_mov_b32_e32 v4, v2
	v_mfma_f32_32x32x16_bf16 v[18:33], v[246:249], v[246:249], 0
	v_mov_b32_e32 v5, v2
	v_mov_b32_e32 v6, v2
	v_mfma_f32_32x32x16_bf16 v[34:49], v[246:249], v[246:249], 0
	v_mov_b32_e32 v7, v2
	v_mov_b32_e32 v8, v2
	v_mfma_f32_32x32x16_bf16 v[50:65], v[246:249], v[246:249], 0
	v_mov_b32_e32 v9, v2
	v_mov_b32_e32 v10, v2
	v_mfma_f32_32x32x16_bf16 v[66:81], v[246:249], v[246:249], 0
	v_mov_b32_e32 v11, v2
	v_mov_b32_e32 v12, v2
	v_mfma_f32_32x32x16_bf16 v[82:97], v[246:249], v[246:249], 0
	v_mov_b32_e32 v13, v2
	v_mov_b32_e32 v14, v2
	v_mfma_f32_32x32x16_bf16 v[98:113], v[246:249], v[246:249], 0
	v_mov_b32_e32 v15, v2
	v_mov_b32_e32 v16, v2
	v_mfma_f32_32x32x16_bf16 v[114:129], v[246:249], v[246:249], 0
	v_mov_b32_e32 v17, v2
	s_nop 0
